# out-proj and down phases: inside each XCD the workgroups with blockIdx bit 6 set (odd column tiles) start 10us later, so the two halves' epilogue read/write bursts do not hit the XCD L2 together
# baseline (speedup 1.0000x reference)
; #define LWS(name) size_t name##_z = 0; asm volatile("" : "+s"(name##_z)); unsigned char* name = p.ws + name##_z
; __device__ __forceinline__ void xcd_barrier(const XcdBarrier& b) {
;     ...
;     }
;     __syncthreads();
; __global__ void __launch_bounds__(512, 2) fwd_megakernel(Params p) {
;     ...
;             LWS(ws);
;             pg8::Gemm g{(const bf16_t*)(ws + WS_MIX), (const bf16_t*)(ws + WS_WOUT) + (size_t)l * DM * DM, MP, DM, DM}; pg8::StaticOrder S; S.init(MP, DM, G, bx);
;             EpiResid E{nullptr, (bf16_t*)(ws + WS_XB), (float*)(ws + WS_SSQB)};
;             pg8::gemm_phase<EpiResid, pg8::StaticOrder, true, true>(lds, g, S, E);
.LBB0_1667:
	s_or_b64 exec, exec, s[6:7]
	s_mov_b64 s[8:9], 0
	s_waitcnt lgkmcnt(0)
	s_barrier
	s_bfe_u32 s100, s2, 0x10006
	s_mul_i32 s100, s100, 1000
	s_memrealtime s[0:1]
	s_waitcnt lgkmcnt(0)
	s_add_u32 s100, s100, s0

; #define LWS(name) size_t name##_z = 0; asm volatile("" : "+s"(name##_z)); unsigned char* name = p.ws + name##_z
; __device__ __forceinline__ void xcd_barrier(const XcdBarrier& b) {
;     ...
;     }
;     __syncthreads();
; __global__ void __launch_bounds__(512, 2) fwd_megakernel(Params p) {
;     ...
;         {
;             LWS(ws);
;             pg8::Gemm g{(const bf16_t*)(ws + WS_HID), (const bf16_t*)(ws + WS_WDN) + (size_t)l * DM * DFF, MP, DM, DFF}; pg8::StaticOrder S; S.init(MP, DM, G, bx);
;             EpiResid E{nullptr, (bf16_t*)(ws + WS_XB), (float*)(ws + WS_SSQA)};
;             pg8::gemm_phase<EpiResid, pg8::StaticOrder, true, true>(lds, g, S, E);
.LBB0_1873:
	s_or_b64 exec, exec, s[8:9]
	s_mov_b64 s[8:9], 0
	s_waitcnt lgkmcnt(0)
	s_barrier
	s_bfe_u32 s100, s2, 0x10006
	s_mul_i32 s100, s100, 1000
	s_memrealtime s[0:1]
	s_waitcnt lgkmcnt(0)
	s_add_u32 s100, s100, s0
